# tail-overlap-P7-P8-arrive-wait-row-repartition
# baseline (speedup 1.0000x reference)
.LBB0_718:
	s_or_b64 exec, exec, s[34:35]
	s_ashr_i32 s31, s30, 31
	s_lshl_b64 s[30:31], s[30:31], 17
	s_lshl_b32 s8, s77, 1
	v_lshl_add_u64 v[70:71], v[138:139], 0, s[30:31]
	s_lshl_b64 s[30:31], s[8:9], 13
	v_lshl_add_u64 v[70:71], v[70:71], 0, s[30:31]
	v_add_co_u32_e32 v72, vcc, 0x2000, v70
	s_nop 1
	v_addc_co_u32_e32 v73, vcc, 0, v71, vcc
	s_barrier
	global_load_dwordx4 v[102:105], v[70:71], off
	global_load_dwordx4 v[98:101], v[72:73], off
	v_add_co_u32_e32 v72, vcc, 0x20000, v70
	s_lshl_b32 s8, s77, 5
	s_nop 0
	v_addc_co_u32_e32 v73, vcc, 0, v71, vcc
	v_add_co_u32_e32 v74, vcc, 0x22000, v70
	s_and_b32 s8, s8, 0x7fffff80
	s_nop 0
	v_addc_co_u32_e32 v75, vcc, 0, v71, vcc
	global_load_dwordx4 v[106:109], v[72:73], off
	global_load_dwordx4 v[94:97], v[74:75], off
	v_add_co_u32_e32 v72, vcc, 0x40000, v70
	v_add_u32_e32 v147, s8, v148
	s_nop 0
	v_addc_co_u32_e32 v73, vcc, 0, v71, vcc
	v_add_co_u32_e32 v74, vcc, 0x42000, v70
	s_lshl_b32 s8, s77, 4
	s_nop 0
	v_addc_co_u32_e32 v75, vcc, 0, v71, vcc
	global_load_dwordx4 v[110:113], v[72:73], off
	global_load_dwordx4 v[90:93], v[74:75], off
	v_add_co_u32_e32 v72, vcc, 0x60000, v70
	v_and_or_b32 v160, s8, 48, v147
	s_nop 0
	v_addc_co_u32_e32 v73, vcc, 0, v71, vcc
	v_add_co_u32_e32 v74, vcc, 0x62000, v70
	v_ashrrev_i32_e32 v161, 31, v160
	s_nop 0
	v_addc_co_u32_e32 v75, vcc, 0, v71, vcc
	global_load_dwordx4 v[114:117], v[72:73], off
	global_load_dwordx4 v[86:89], v[74:75], off
	v_add_co_u32_e32 v72, vcc, 0x80000, v70
	v_ashrrev_i32_e32 v147, 31, v146
	s_nop 0
	v_addc_co_u32_e32 v73, vcc, 0, v71, vcc
	v_add_co_u32_e32 v74, vcc, 0x82000, v70
	s_mov_b64 s[30:31], 0
	s_nop 0
	v_addc_co_u32_e32 v75, vcc, 0, v71, vcc
	global_load_dwordx4 v[118:121], v[72:73], off
	global_load_dwordx4 v[82:85], v[74:75], off
	v_add_co_u32_e32 v72, vcc, 0xa0000, v70
	s_waitcnt vmcnt(9)
	v_lshlrev_b32_e32 v162, 16, v102
	v_addc_co_u32_e32 v73, vcc, 0, v71, vcc
	v_add_co_u32_e32 v74, vcc, 0xa2000, v70
	v_and_b32_e32 v163, 0xffff0000, v102
	s_nop 0
	v_addc_co_u32_e32 v75, vcc, 0, v71, vcc
	global_load_dwordx4 v[122:125], v[72:73], off
	global_load_dwordx4 v[78:81], v[74:75], off
	v_add_co_u32_e32 v72, vcc, 0xc0000, v70
	v_lshlrev_b32_e32 v102, 16, v103
	s_nop 0
	v_addc_co_u32_e32 v73, vcc, 0, v71, vcc
	v_add_co_u32_e32 v74, vcc, 0xc2000, v70
	v_and_b32_e32 v103, 0xffff0000, v103
	s_nop 0
	v_addc_co_u32_e32 v75, vcc, 0, v71, vcc
	global_load_dwordx4 v[126:129], v[72:73], off
	s_nop 0
	global_load_dwordx4 v[74:77], v[74:75], off
	v_add_co_u32_e32 v72, vcc, 0xe0000, v70
	v_pk_add_f32 v[162:163], v[162:163], 0 op_sel_hi:[1,0]
	s_nop 0
	v_addc_co_u32_e32 v73, vcc, 0, v71, vcc
	v_add_co_u32_e32 v70, vcc, 0xe2000, v70
	v_pk_add_f32 v[102:103], v[102:103], 0 op_sel_hi:[1,0]
	s_nop 0
	v_addc_co_u32_e32 v71, vcc, 0, v71, vcc
	global_load_dwordx4 v[156:159], v[72:73], off
	s_nop 0
	global_load_dwordx4 v[70:73], v[70:71], off
	v_lshlrev_b32_e32 v164, 16, v104
	v_and_b32_e32 v165, 0xffff0000, v104
	v_lshlrev_b32_e32 v104, 16, v105
	v_and_b32_e32 v105, 0xffff0000, v105
	s_waitcnt vmcnt(13)
	v_lshlrev_b32_e32 v166, 16, v106
	v_and_b32_e32 v167, 0xffff0000, v106
	v_lshlrev_b32_e32 v106, 16, v107
	v_and_b32_e32 v107, 0xffff0000, v107
	v_pk_add_f32 v[164:165], v[164:165], 0 op_sel_hi:[1,0]
	v_pk_add_f32 v[104:105], v[104:105], 0 op_sel_hi:[1,0]
	v_pk_add_f32 v[102:103], v[102:103], v[106:107]
	v_pk_add_f32 v[106:107], v[162:163], v[166:167]
	v_lshlrev_b32_e32 v162, 16, v108
	v_and_b32_e32 v163, 0xffff0000, v108
	v_lshlrev_b32_e32 v108, 16, v109
	v_and_b32_e32 v109, 0xffff0000, v109
	v_pk_add_f32 v[104:105], v[104:105], v[108:109]
	v_pk_add_f32 v[108:109], v[164:165], v[162:163]
	s_waitcnt vmcnt(11)
	v_lshlrev_b32_e32 v162, 16, v110
	v_and_b32_e32 v163, 0xffff0000, v110
	v_lshlrev_b32_e32 v110, 16, v111
	v_and_b32_e32 v111, 0xffff0000, v111
	v_pk_add_f32 v[102:103], v[102:103], v[110:111]
	v_lshlrev_b32_e32 v110, 16, v112
	v_and_b32_e32 v111, 0xffff0000, v112
	v_lshlrev_b32_e32 v112, 16, v113
	v_and_b32_e32 v113, 0xffff0000, v113
	v_pk_add_f32 v[106:107], v[106:107], v[162:163]
	v_pk_add_f32 v[108:109], v[108:109], v[110:111]
	v_pk_add_f32 v[104:105], v[104:105], v[112:113]
	s_waitcnt vmcnt(9)
	v_lshlrev_b32_e32 v110, 16, v114
	v_and_b32_e32 v111, 0xffff0000, v114
	v_lshlrev_b32_e32 v112, 16, v115
	v_and_b32_e32 v113, 0xffff0000, v115
	v_pk_add_f32 v[102:103], v[102:103], v[112:113]
	v_pk_add_f32 v[106:107], v[106:107], v[110:111]
	v_lshlrev_b32_e32 v110, 16, v116
	v_and_b32_e32 v111, 0xffff0000, v116
	v_lshlrev_b32_e32 v112, 16, v117
	v_and_b32_e32 v113, 0xffff0000, v117
	v_pk_add_f32 v[104:105], v[104:105], v[112:113]
	v_pk_add_f32 v[108:109], v[108:109], v[110:111]
	s_waitcnt vmcnt(7)
	v_lshlrev_b32_e32 v110, 16, v118
	v_and_b32_e32 v111, 0xffff0000, v118
	v_lshlrev_b32_e32 v112, 16, v119
	v_and_b32_e32 v113, 0xffff0000, v119
	v_pk_add_f32 v[106:107], v[106:107], v[110:111]
	v_pk_add_f32 v[102:103], v[102:103], v[112:113]
	v_lshlrev_b32_e32 v110, 16, v120
	v_and_b32_e32 v111, 0xffff0000, v120
	v_lshlrev_b32_e32 v112, 16, v121
	v_and_b32_e32 v113, 0xffff0000, v121
	v_pk_add_f32 v[108:109], v[108:109], v[110:111]
	v_pk_add_f32 v[104:105], v[104:105], v[112:113]
	s_waitcnt vmcnt(5)
	v_lshlrev_b32_e32 v110, 16, v122
	v_and_b32_e32 v111, 0xffff0000, v122
	v_lshlrev_b32_e32 v112, 16, v123
	v_and_b32_e32 v113, 0xffff0000, v123
	v_pk_add_f32 v[102:103], v[102:103], v[112:113]
	v_pk_add_f32 v[106:107], v[106:107], v[110:111]
	v_lshlrev_b32_e32 v110, 16, v124
	v_and_b32_e32 v111, 0xffff0000, v124
	v_lshlrev_b32_e32 v112, 16, v125
	v_and_b32_e32 v113, 0xffff0000, v125
	v_pk_add_f32 v[104:105], v[104:105], v[112:113]
	v_pk_add_f32 v[108:109], v[108:109], v[110:111]
	s_waitcnt vmcnt(3)
	v_lshlrev_b32_e32 v110, 16, v126
	v_and_b32_e32 v111, 0xffff0000, v126
	v_lshlrev_b32_e32 v112, 16, v127
	v_and_b32_e32 v113, 0xffff0000, v127
	v_pk_add_f32 v[106:107], v[106:107], v[110:111]
	v_pk_add_f32 v[102:103], v[102:103], v[112:113]
	v_lshlrev_b32_e32 v110, 16, v128
	v_and_b32_e32 v111, 0xffff0000, v128
	v_lshlrev_b32_e32 v112, 16, v129
	v_and_b32_e32 v113, 0xffff0000, v129
	v_pk_add_f32 v[108:109], v[108:109], v[110:111]
	v_pk_add_f32 v[104:105], v[104:105], v[112:113]
	s_waitcnt vmcnt(1)
	v_lshlrev_b32_e32 v110, 16, v156
	v_and_b32_e32 v111, 0xffff0000, v156
	v_lshlrev_b32_e32 v112, 16, v157
	v_and_b32_e32 v113, 0xffff0000, v157
	v_pk_add_f32 v[102:103], v[102:103], v[112:113]
	v_pk_add_f32 v[106:107], v[106:107], v[110:111]
	v_lshlrev_b32_e32 v110, 16, v158
	v_and_b32_e32 v111, 0xffff0000, v158
	v_lshlrev_b32_e32 v112, 16, v159
	v_and_b32_e32 v113, 0xffff0000, v159
	v_pk_add_f32 v[112:113], v[104:105], v[112:113]
	v_pk_add_f32 v[108:109], v[108:109], v[110:111]
	v_cvt_pk_bf16_f32 v105, v102, v103
	v_lshlrev_b64 v[102:103], 12, v[160:161]
	v_cvt_pk_bf16_f32 v104, v106, v107
	v_cvt_pk_bf16_f32 v106, v108, v109
	v_lshl_add_u64 v[108:109], s[40:41], 0, v[102:103]
	v_cvt_pk_bf16_f32 v107, v112, v113
	v_lshl_add_u64 v[108:109], v[146:147], 1, v[108:109]
	global_store_dwordx4 v[108:109], v[104:107], off sc1
	v_lshlrev_b32_e32 v108, 16, v94
	v_and_b32_e32 v109, 0xffff0000, v94
	v_lshlrev_b32_e32 v104, 16, v98
	v_and_b32_e32 v105, 0xffff0000, v98
	v_lshlrev_b32_e32 v98, 16, v99
	v_and_b32_e32 v99, 0xffff0000, v99
	v_pk_add_f32 v[104:105], v[104:105], 0 op_sel_hi:[1,0]
	v_pk_add_f32 v[98:99], v[98:99], 0 op_sel_hi:[1,0]
	v_lshlrev_b32_e32 v106, 16, v100
	v_and_b32_e32 v107, 0xffff0000, v100
	v_lshlrev_b32_e32 v100, 16, v101
	v_and_b32_e32 v101, 0xffff0000, v101
	v_lshlrev_b32_e32 v94, 16, v95
	v_and_b32_e32 v95, 0xffff0000, v95
	v_pk_add_f32 v[106:107], v[106:107], 0 op_sel_hi:[1,0]
	v_pk_add_f32 v[100:101], v[100:101], 0 op_sel_hi:[1,0]
	v_pk_add_f32 v[94:95], v[98:99], v[94:95]
	v_pk_add_f32 v[98:99], v[104:105], v[108:109]
	v_lshlrev_b32_e32 v104, 16, v96
	v_and_b32_e32 v105, 0xffff0000, v96
	v_lshlrev_b32_e32 v96, 16, v97
	v_and_b32_e32 v97, 0xffff0000, v97
	v_pk_add_f32 v[96:97], v[100:101], v[96:97]
	v_pk_add_f32 v[100:101], v[106:107], v[104:105]
	v_lshlrev_b32_e32 v104, 16, v90
	v_and_b32_e32 v105, 0xffff0000, v90
	v_lshlrev_b32_e32 v90, 16, v91
	v_and_b32_e32 v91, 0xffff0000, v91
	v_pk_add_f32 v[90:91], v[94:95], v[90:91]
	v_lshlrev_b32_e32 v94, 16, v92
	v_and_b32_e32 v95, 0xffff0000, v92
	v_lshlrev_b32_e32 v92, 16, v93
	v_and_b32_e32 v93, 0xffff0000, v93
	v_pk_add_f32 v[98:99], v[98:99], v[104:105]
	v_pk_add_f32 v[92:93], v[96:97], v[92:93]
	v_lshlrev_b32_e32 v96, 16, v86
	v_and_b32_e32 v97, 0xffff0000, v86
	v_lshlrev_b32_e32 v86, 16, v87
	v_and_b32_e32 v87, 0xffff0000, v87
	v_pk_add_f32 v[94:95], v[100:101], v[94:95]
	v_pk_add_f32 v[86:87], v[90:91], v[86:87]
	v_pk_add_f32 v[90:91], v[98:99], v[96:97]
	v_lshlrev_b32_e32 v96, 16, v88
	v_and_b32_e32 v97, 0xffff0000, v88
	v_lshlrev_b32_e32 v88, 16, v89
	v_and_b32_e32 v89, 0xffff0000, v89
	v_pk_add_f32 v[88:89], v[92:93], v[88:89]
	v_pk_add_f32 v[92:93], v[94:95], v[96:97]
	v_lshlrev_b32_e32 v94, 16, v82
	v_and_b32_e32 v95, 0xffff0000, v82
	v_lshlrev_b32_e32 v82, 16, v83
	v_and_b32_e32 v83, 0xffff0000, v83
	v_pk_add_f32 v[82:83], v[86:87], v[82:83]
	v_lshlrev_b32_e32 v86, 16, v84
	v_and_b32_e32 v87, 0xffff0000, v84
	v_lshlrev_b32_e32 v84, 16, v85
	v_and_b32_e32 v85, 0xffff0000, v85
	v_pk_add_f32 v[90:91], v[90:91], v[94:95]
	v_pk_add_f32 v[84:85], v[88:89], v[84:85]
	v_lshlrev_b32_e32 v88, 16, v78
	v_and_b32_e32 v89, 0xffff0000, v78
	v_lshlrev_b32_e32 v78, 16, v79
	v_and_b32_e32 v79, 0xffff0000, v79
	v_pk_add_f32 v[86:87], v[92:93], v[86:87]
	v_pk_add_f32 v[78:79], v[82:83], v[78:79]
	v_pk_add_f32 v[82:83], v[90:91], v[88:89]
	v_lshlrev_b32_e32 v88, 16, v80
	v_and_b32_e32 v89, 0xffff0000, v80
	v_lshlrev_b32_e32 v80, 16, v81
	v_and_b32_e32 v81, 0xffff0000, v81
	v_pk_add_f32 v[80:81], v[84:85], v[80:81]
	v_pk_add_f32 v[84:85], v[86:87], v[88:89]
	v_lshlrev_b32_e32 v86, 16, v74
	v_and_b32_e32 v87, 0xffff0000, v74
	v_lshlrev_b32_e32 v74, 16, v75
	v_and_b32_e32 v75, 0xffff0000, v75
	v_pk_add_f32 v[74:75], v[78:79], v[74:75]
	v_lshlrev_b32_e32 v78, 16, v76
	v_and_b32_e32 v79, 0xffff0000, v76
	v_lshlrev_b32_e32 v76, 16, v77
	v_and_b32_e32 v77, 0xffff0000, v77
	v_pk_add_f32 v[78:79], v[84:85], v[78:79]
	s_waitcnt vmcnt(1)
	v_lshlrev_b32_e32 v84, 16, v70
	v_and_b32_e32 v85, 0xffff0000, v70
	v_lshlrev_b32_e32 v70, 16, v71
	v_and_b32_e32 v71, 0xffff0000, v71
	v_pk_add_f32 v[82:83], v[82:83], v[86:87]
	v_pk_add_f32 v[80:81], v[80:81], v[76:77]
	v_pk_add_f32 v[76:77], v[74:75], v[70:71]
	v_lshlrev_b32_e32 v70, 16, v72
	v_and_b32_e32 v71, 0xffff0000, v72
	v_lshlrev_b32_e32 v72, 16, v73
	v_and_b32_e32 v73, 0xffff0000, v73
	v_pk_add_f32 v[74:75], v[82:83], v[84:85]
	v_pk_add_f32 v[72:73], v[80:81], v[72:73]
	v_pk_add_f32 v[70:71], v[78:79], v[70:71]

.LBB0_721:
	v_lshl_add_u64 v[6:7], s[40:41], 0, v[102:103]
	v_cvt_pk_bf16_f32 v2, v74, v75
	v_cvt_pk_bf16_f32 v3, v76, v77
	v_cvt_pk_bf16_f32 v4, v70, v71
	v_cvt_pk_bf16_f32 v5, v72, v73
	v_lshl_add_u64 v[6:7], v[146:147], 1, v[6:7]
	s_and_b64 vcc, exec, s[4:5]
	s_mov_b64 s[30:31], -1
	global_store_dwordx4 v[6:7], v[2:5], off offset:256 sc1
	s_waitcnt vmcnt(0)
	s_mov_b64 s[100:101], exec
	s_mov_b64 exec, 1
	v_mov_b32_e32 v245, 1
	s_cmp_lt_i32 s77, 0
	s_cbranch_scc1 .LtovA_7
	v_mov_b32_e32 v244, 0xa880
	s_branch .LtovG_7
.LtovA_7:
	v_readlane_b32 s98, v242, 30
	s_lshl_b32 s98, s98, 6
	s_add_u32 s98, s98, 0xa000
	v_mov_b32_e32 v244, s98
.LtovG_7:
	global_atomic_add v244, v245, s[70:71]
	s_mov_b64 exec, s[100:101]
	s_and_b64 vcc, exec, s[4:5]
	s_cbranch_vccnz .LBB0_696
	s_andn2_b64 vcc, exec, s[10:11]
	s_cbranch_vccnz .LBB0_695
	s_barrier
	s_branch .LBB0_695

.LBB0_725:
	s_cmp_gt_i32 s73, 8
	s_cselect_b64 s[0:1], -1, 0
	s_and_b64 s[4:5], s[6:7], s[0:1]
	v_readlane_b32 s14, v242, 47
	s_andn2_b64 vcc, exec, s[4:5]
	v_readlane_b32 s15, v242, 48
	s_cbranch_vccnz .LBB0_789
	s_cmp_gt_i32 s72, -1
	s_mov_b64 s[4:5], -1
	s_cbranch_scc0 .LBB0_776
	s_waitcnt vmcnt(0)
	v_cmp_eq_u32_e32 vcc, 0, v143
	s_waitcnt vmcnt(0)
	s_barrier
	s_and_saveexec_b64 s[4:5], vcc
	s_cbranch_execz .LBB0_775
	v_readlane_b32 s98, v242, 30
	v_readlane_b32 s3, v242, 11
	s_nop 2
	v_mov_b32_e32 v1, s3
	ds_read_b32 v3, v1
	ds_read_b32 v4, v1 offset:4
	s_lshl_b32 s98, s98, 6
	s_add_u32 s99, s98, 0xa000
	s_add_u32 s98, s98, 0xa400
	v_mov_b32_e32 v5, s99
	v_mov_b32_e32 v7, s98
	v_mov_b32_e32 v8, 1
	s_waitcnt lgkmcnt(0)
	v_lshlrev_b32_e32 v3, 3, v3
	s_mov_b32 s99, 0
.LtovW1_7:
	global_load_dword v6, v5, s[70:71] sc1
	s_waitcnt vmcnt(0)
	v_cmp_eq_u32_e32 vcc, v6, v3
	s_cbranch_vccnz .LtovW1d_7
	s_sleep 1
	s_add_u32 s99, s99, 1
	s_cmp_lt_u32 s99, 0x20000
	s_cbranch_scc1 .LtovW1_7
.LtovW1d_7:
	global_atomic_add v9, v7, v8, s[70:71] sc0
	s_waitcnt vmcnt(0)
	v_cmp_eq_u32_e32 vcc, 0, v9
	s_cbranch_vccz .LtovNF_7
	buffer_wbl2 sc1
	s_waitcnt vmcnt(0)
	v_mov_b32_e32 v7, 0xa800
	global_atomic_add v9, v7, v8, s[70:71] sc0
	s_waitcnt vmcnt(0)
	v_add_u32_e32 v9, 1, v9
	v_cmp_eq_u32_e32 vcc, v9, v4
	s_cbranch_vccz .LtovNF_7
	v_mov_b32_e32 v7, 0xa840
	global_store_dword v7, v8, s[70:71] sc1
.LtovNF_7:
	v_mov_b32_e32 v5, 0xa840
	s_mov_b32 s99, 0
.LtovW2_7:
	global_load_dword v6, v5, s[70:71] sc1
	s_waitcnt vmcnt(0)
	v_cmp_ne_u32_e32 vcc, 0, v6
	s_cbranch_vccnz .LtovW2d_7
	s_sleep 1
	s_add_u32 s99, s99, 1
	s_cmp_lt_u32 s99, 0x20000
	s_cbranch_scc1 .LtovW2_7
.LtovW2d_7:
	s_cmp_lt_u32 s2, 128
	s_cbranch_scc0 .LtovW3d_7
	v_mov_b32_e32 v5, 0xa880
	v_mov_b32_e32 v3, 0x400
	s_mov_b32 s99, 0

.LtovW3d_7:
	buffer_inv sc1
	s_waitcnt vmcnt(0)
	s_branch .LBB0_775
	v_readlane_b32 s3, v242, 11
	s_waitcnt vmcnt(0) expcnt(0) lgkmcnt(0)
	s_nop 0
	v_mov_b32_e32 v1, s3
	ds_read_b32 v3, v1
	ds_read_b32 v1, v1 offset:4
	s_waitcnt lgkmcnt(1)
	v_cmp_ne_u32_e32 vcc, 0, v3
	s_cbranch_vccnz .LBB0_743
	s_add_u32 s6, s70, 0x1000
	s_addc_u32 s7, s71, 0
	s_add_u32 s8, s70, 0x1100
	s_addc_u32 s9, s71, 0
	s_add_u32 s10, s70, 0x1200
	v_readlane_b32 s3, v242, 8
	s_addc_u32 s11, s71, 0
	s_mul_i32 s3, s75, s3
	s_add_u32 s12, s70, 0x1300
	s_mul_i32 s3, s3, s74
	s_addc_u32 s13, s71, 0
	s_mov_b32 s24, 1
	v_mov_b32_e32 v17, 0
	s_branch .LBB0_731

.LBB0_788:
.LBB0_789:
	v_writelane_b32 v240, s56, 2
	v_writelane_b32 v240, s64, 3
	s_cmp_lt_i32 s72, 9
	s_cselect_b64 s[4:5], -1, 0
	s_and_b64 s[0:1], s[4:5], s[0:1]
	s_andn2_b64 vcc, exec, s[0:1]
	s_cbranch_vccnz .LBB0_796
	s_cmp_lt_u32 s2, 128
	s_cbranch_scc1 .LtovL_7
	s_sub_u32 s56, s56, 1024
	s_mov_b32 s100, 6144
	s_branch .LtovC_7
.LtovL_7:
	s_add_u32 s56, s56, 6144
	s_mov_b32 s100, 8704
.LtovC_7:
	s_mov_b32 s64, 1024
	s_cmp_ge_i32 s56, s100
	s_cbranch_scc1 .LBB0_796
	v_readlane_b32 s76, v242, 12
	v_readlane_b32 s77, v242, 13
	v_readlane_b32 s78, v242, 14
	v_readlane_b32 s79, v242, 15
	v_readlane_b32 s80, v242, 16
	v_readlane_b32 s81, v242, 17
	v_readlane_b32 s82, v242, 18
	v_readlane_b32 s83, v242, 19
	v_readlane_b32 s84, v242, 20
	v_readlane_b32 s85, v242, 21
	v_readlane_b32 s86, v242, 22
	v_readlane_b32 s87, v242, 23
	v_readlane_b32 s88, v242, 24
	v_readlane_b32 s89, v242, 25
	v_readlane_b32 s90, v242, 26
	v_readlane_b32 s91, v242, 27
	s_mov_b64 s[8:9], s[76:77]
	s_mov_b64 s[18:19], s[86:87]
	v_readlane_b32 s76, v242, 31
	s_waitcnt vmcnt(0)
	v_lshlrev_b32_e32 v98, 4, v142
	v_mov_b32_e32 v99, 0
	v_readlane_b32 s86, v242, 41
	v_readlane_b32 s87, v242, 42
	v_lshl_add_u64 v[50:51], s[8:9], 0, v[98:99]
	s_mov_b64 s[4:5], 0x2000
	v_lshl_add_u64 v[52:53], s[86:87], 0, v[98:99]
	v_add_co_u32_e32 v34, vcc, 0x2000, v52
	v_lshl_add_u64 v[38:39], v[52:53], 0, s[4:5]
	s_nop 0
	v_addc_co_u32_e32 v35, vcc, 0, v53, vcc
	v_add_co_u32_e32 v78, vcc, 0x1000, v50
	global_load_dwordx4 v[2:5], v98, s[8:9]
	global_load_dwordx4 v[6:9], v98, s[18:19]
	global_load_dwordx4 v[10:13], v98, s[8:9] offset:1024
	global_load_dwordx4 v[14:17], v98, s[18:19] offset:1024
	global_load_dwordx4 v[18:21], v[38:39], off offset:1024
	global_load_dwordx4 v[22:25], v[38:39], off offset:2048
	global_load_dwordx4 v[26:29], v98, s[8:9] offset:2048
	global_load_dwordx4 v[30:33], v98, s[18:19] offset:2048
	s_nop 0
	global_load_dwordx4 v[34:37], v[34:35], off
	s_nop 0
	global_load_dwordx4 v[38:41], v[38:39], off offset:3072
	s_nop 0
	global_load_dwordx4 v[42:45], v98, s[8:9] offset:3072
	global_load_dwordx4 v[46:49], v98, s[18:19] offset:3072
	v_addc_co_u32_e32 v79, vcc, 0, v51, vcc
	v_add_co_u32_e32 v86, vcc, 0x3000, v52
	v_lshl_add_u64 v[54:55], s[18:19], 0, v[98:99]
	s_nop 0
	v_addc_co_u32_e32 v87, vcc, 0, v53, vcc
	v_add_co_u32_e32 v94, vcc, 0x1000, v54
	s_ashr_i32 s57, s56, 31
	s_nop 0
	v_addc_co_u32_e32 v95, vcc, 0, v55, vcc
	global_load_dwordx4 v[50:53], v[78:79], off
	global_load_dwordx4 v[54:57], v[78:79], off offset:1024
	global_load_dwordx4 v[58:61], v[86:87], off
	global_load_dwordx4 v[62:65], v[86:87], off offset:1024
	global_load_dwordx4 v[66:69], v[94:95], off
	global_load_dwordx4 v[70:73], v[94:95], off offset:1024
	global_load_dwordx4 v[74:77], v[78:79], off offset:2048
	s_nop 0
	global_load_dwordx4 v[78:81], v[78:79], off offset:3072
	s_lshl_b64 s[4:5], s[56:57], 12
	v_readlane_b32 s6, v242, 51
	v_readlane_b32 s7, v242, 52
	s_add_u32 s6, s6, s4
	s_addc_u32 s7, s7, s5
	s_add_u32 s8, s40, s4
	v_lshlrev_b32_e32 v98, 3, v142
	s_addc_u32 s9, s41, s5
	global_load_dwordx2 v[154:155], v98, s[8:9] offset:2048
	global_load_dwordx2 v[152:153], v98, s[8:9] offset:2560
	global_load_dwordx2 v[150:151], v98, s[8:9] offset:3072
	global_load_dwordx2 v[148:149], v98, s[8:9] offset:3584
	global_load_dwordx2 v[162:163], v98, s[8:9]
	global_load_dwordx2 v[160:161], v98, s[8:9] offset:512
	global_load_dwordx2 v[158:159], v98, s[8:9] offset:1024
	global_load_dwordx2 v[156:157], v98, s[8:9] offset:1536
	global_load_dwordx4 v[82:85], v[86:87], off offset:2048
	s_nop 0
	global_load_dwordx4 v[86:89], v[86:87], off offset:3072
	s_nop 0
	global_load_dwordx2 v[164:165], v98, s[6:7]
	global_load_dwordx2 v[146:147], v98, s[6:7] offset:512
	global_load_dwordx2 v[144:145], v98, s[6:7] offset:1024
	global_load_dwordx2 v[140:141], v98, s[6:7] offset:1536
	global_load_dwordx2 v[138:139], v98, s[6:7] offset:2048
	global_load_dwordx2 v[136:137], v98, s[6:7] offset:2560
	global_load_dwordx2 v[134:135], v98, s[6:7] offset:3072
	global_load_dwordx2 v[132:133], v98, s[6:7] offset:3584
	global_load_dwordx4 v[90:93], v[94:95], off offset:2048
	s_nop 0
	global_load_dwordx4 v[94:97], v[94:95], off offset:3072
	v_mbcnt_lo_u32_b32 v1, -1, 0
	v_mbcnt_hi_u32_b32 v100, -1, v1
	v_and_b32_e32 v1, 64, v100
	v_add_u32_e32 v101, 64, v1
	v_xor_b32_e32 v1, 1, v100
	v_cmp_lt_i32_e32 vcc, v1, v101
	v_xor_b32_e32 v102, 2, v100
	s_add_u32 s4, s70, s4
	v_cndmask_b32_e32 v1, v100, v1, vcc
	v_cmp_lt_i32_e32 vcc, v102, v101
	s_addc_u32 s5, s71, s5
	s_add_i32 s8, s56, s64
	v_cndmask_b32_e32 v102, v100, v102, vcc
	v_lshlrev_b32_e32 v166, 2, v102
	v_xor_b32_e32 v102, 4, v100
	v_cmp_lt_i32_e32 vcc, v102, v101
	s_ashr_i32 s65, s64, 31
	s_ashr_i32 s9, s8, 31
	v_cndmask_b32_e32 v102, v100, v102, vcc
	v_lshlrev_b32_e32 v167, 2, v102
	v_xor_b32_e32 v102, 8, v100
	v_cmp_lt_i32_e32 vcc, v102, v101
	s_lshl_b64 s[6:7], s[64:65], 12
	s_lshl_b64 s[8:9], s[8:9], 12
	v_cndmask_b32_e32 v102, v100, v102, vcc
	v_lshlrev_b32_e32 v168, 2, v102
	v_xor_b32_e32 v102, 16, v100
	v_cmp_lt_i32_e32 vcc, v102, v101
	s_add_u32 s8, s70, s8
	v_lshlrev_b32_e32 v1, 2, v1
	v_cndmask_b32_e32 v102, v100, v102, vcc
	v_lshlrev_b32_e32 v169, 2, v102
	v_xor_b32_e32 v102, 32, v100
	v_cmp_lt_i32_e32 vcc, v102, v101
	s_addc_u32 s9, s71, s9
	s_mov_b32 s3, 0x1d000000
	v_cndmask_b32_e32 v100, v100, v102, vcc
	v_lshlrev_b32_e32 v170, 2, v100
	v_mov_b32_e32 v171, 0x358637bd
	s_mov_b32 s12, 0x800000
	s_brev_b32 s13, 48
	s_mov_b32 s18, 0x14800000
	s_mov_b32 s19, s56
	v_readlane_b32 s77, v242, 32
	v_readlane_b32 s78, v242, 33
	v_readlane_b32 s79, v242, 34
	v_readlane_b32 s80, v242, 35
	v_readlane_b32 s81, v242, 36
	v_readlane_b32 s82, v242, 37
	v_readlane_b32 s83, v242, 38
	v_readlane_b32 s84, v242, 39
	v_readlane_b32 s85, v242, 40
	v_readlane_b32 s88, v242, 43
	v_readlane_b32 s89, v242, 44
	v_readlane_b32 s90, v242, 45
	v_readlane_b32 s91, v242, 46
	s_waitcnt vmcnt(19)
	v_mov_b64_e32 v[118:119], v[154:155]
	s_waitcnt vmcnt(18)
	v_mov_b64_e32 v[116:117], v[152:153]
	s_waitcnt vmcnt(17)
	v_mov_b64_e32 v[114:115], v[150:151]
	s_waitcnt vmcnt(16)
	v_mov_b64_e32 v[112:113], v[148:149]
	s_waitcnt vmcnt(15)
	v_mov_b64_e32 v[126:127], v[162:163]
	s_waitcnt vmcnt(14)
	v_mov_b64_e32 v[124:125], v[160:161]
	s_waitcnt vmcnt(13)
	v_mov_b64_e32 v[122:123], v[158:159]
	s_waitcnt vmcnt(12)
	v_mov_b64_e32 v[120:121], v[156:157]
	s_waitcnt vmcnt(9)
	v_mov_b64_e32 v[100:101], v[164:165]
	s_waitcnt vmcnt(8)
	v_mov_b64_e32 v[102:103], v[146:147]
	s_waitcnt vmcnt(7)
	v_mov_b64_e32 v[104:105], v[144:145]
	s_waitcnt vmcnt(6)
	v_mov_b64_e32 v[106:107], v[140:141]
	s_waitcnt vmcnt(5)
	v_mov_b64_e32 v[108:109], v[138:139]
	s_waitcnt vmcnt(4)
	v_mov_b64_e32 v[110:111], v[136:137]
	s_waitcnt vmcnt(3)
	v_mov_b64_e32 v[128:129], v[134:135]
	s_waitcnt vmcnt(2)
	v_mov_b64_e32 v[130:131], v[132:133]
	s_branch .LBB0_793

.LBB0_793:
	s_add_i32 s19, s19, s64
	s_cmp_ge_i32 s19, s100
	s_cselect_b64 s[10:11], -1, 0
	s_and_b64 vcc, exec, s[10:11]
	s_cbranch_vccnz .LBB0_792
	v_lshl_add_u64 v[112:113], s[8:9], 0, v[98:99]
	v_add_co_u32_e32 v114, vcc, 0x1d000000, v112
	s_nop 1
	v_addc_co_u32_e32 v115, vcc, 0, v113, vcc
	v_add_co_u32_e32 v112, vcc, 0xe200000, v112
	global_load_dwordx2 v[100:101], v[114:115], off
	global_load_dwordx2 v[102:103], v[114:115], off offset:512
	global_load_dwordx2 v[104:105], v[114:115], off offset:1024
	global_load_dwordx2 v[106:107], v[114:115], off offset:1536
	global_load_dwordx2 v[108:109], v[114:115], off offset:2048
	global_load_dwordx2 v[110:111], v[114:115], off offset:2560
	global_load_dwordx2 v[128:129], v[114:115], off offset:3072
	global_load_dwordx2 v[130:131], v[114:115], off offset:3584
	v_addc_co_u32_e32 v113, vcc, 0, v113, vcc
	global_load_dwordx2 v[126:127], v[112:113], off
	global_load_dwordx2 v[124:125], v[112:113], off offset:512
	global_load_dwordx2 v[122:123], v[112:113], off offset:1024
	global_load_dwordx2 v[120:121], v[112:113], off offset:1536
	global_load_dwordx2 v[118:119], v[112:113], off offset:2048
	global_load_dwordx2 v[116:117], v[112:113], off offset:2560
	global_load_dwordx2 v[114:115], v[112:113], off offset:3072
	s_nop 0
	global_load_dwordx2 v[112:113], v[112:113], off offset:3584
	s_branch .LBB0_792

.LBB0_796:
	v_readlane_b32 s56, v240, 2
	v_readlane_b32 s64, v240, 3
	s_cmp_gt_i32 s73, 9
	s_cselect_b64 s[4:5], -1, 0
	s_and_b64 s[0:1], s[0:1], s[4:5]
	s_andn2_b64 vcc, exec, s[0:1]
	s_cbranch_vccnz .LBB0_860
	s_cmp_gt_i32 s72, -1
	s_mov_b64 s[0:1], -1
	s_cbranch_scc0 .LBB0_847
	s_waitcnt vmcnt(0)
	v_cmp_eq_u32_e32 vcc, 0, v143
	s_waitcnt vmcnt(0)
	s_barrier
	s_and_saveexec_b64 s[0:1], vcc
	s_cbranch_execz .LBB0_846
	v_readlane_b32 s3, v242, 11
	s_waitcnt vmcnt(0) expcnt(0) lgkmcnt(0)
	s_nop 0
	v_mov_b32_e32 v1, s3
	ds_read_b32 v3, v1
	ds_read_b32 v1, v1 offset:4
	s_waitcnt lgkmcnt(1)
	v_cmp_ne_u32_e32 vcc, 0, v3
	s_cbranch_vccnz .LBB0_814
	s_add_u32 s6, s70, 0x1000
	s_addc_u32 s7, s71, 0
	s_add_u32 s8, s70, 0x1100
	s_addc_u32 s9, s71, 0
	s_add_u32 s10, s70, 0x1200
	v_readlane_b32 s3, v242, 8
	s_addc_u32 s11, s71, 0
	s_mul_i32 s3, s75, s3
	s_add_u32 s12, s70, 0x1300
	s_mul_i32 s3, s3, s74
	s_addc_u32 s13, s71, 0
	s_mov_b32 s24, 1
	v_mov_b32_e32 v17, 0
	s_branch .LBB0_802

.LBB0_1064:
	s_lshl_b32 s3, s65, 8
	s_add_u32 s6, s70, s3
	s_addc_u32 s7, s71, 0
	v_mov_b32_e32 v2, 0x1000
	v_mov_b32_e32 v4, 1
	global_atomic_add v4, v2, v4, s[6:7] offset:1024 sc0
	v_cvt_f32_u32_e32 v2, v3
	v_sub_u32_e32 v5, 0, v3
	v_rcp_iflag_f32_e32 v2, v2
	s_nop 0
	v_mul_f32_e32 v2, 0x4f7ffffe, v2
	v_cvt_u32_f32_e32 v2, v2
	v_mul_lo_u32 v5, v5, v2
	v_mul_hi_u32 v5, v2, v5
	v_add_u32_e32 v2, v2, v5
	s_waitcnt vmcnt(0)
	v_mul_hi_u32 v2, v4, v2
	v_mul_lo_u32 v5, v2, v3
	v_sub_u32_e32 v5, v4, v5
	v_add_u32_e32 v6, 1, v2
	v_cmp_ge_u32_e32 vcc, v5, v3
	v_add_u32_e32 v4, 1, v4
	s_nop 0
	v_cndmask_b32_e32 v2, v2, v6, vcc
	v_sub_u32_e32 v6, v5, v3
	v_cndmask_b32_e32 v5, v5, v6, vcc
	v_add_u32_e32 v6, 1, v2
	v_cmp_ge_u32_e32 vcc, v5, v3
	s_nop 1
	v_cndmask_b32_e32 v2, v2, v6, vcc
	v_mul_lo_u32 v5, v3, v2
	v_add_u32_e32 v3, v5, v3
	v_cmp_ne_u32_e32 vcc, v4, v3
	s_and_saveexec_b64 s[8:9], vcc
	s_xor_b64 s[8:9], exec, s[8:9]
	s_cbranch_execz .LBB0_1078
	s_waitcnt lgkmcnt(0)
	v_mov_b32_e32 v1, 0x3500
	global_load_dword v1, v1, s[70:71] sc1
	s_add_u32 s12, s70, 0x3500
	s_addc_u32 s13, s71, 0
	v_mov_b32_e32 v2, 7
	s_waitcnt vmcnt(0)
	v_cmp_eq_u32_e32 vcc, v1, v2
	s_and_saveexec_b64 s[10:11], vcc
	s_cbranch_execz .LBB0_1077
	s_mov_b32 s3, 1
	s_mov_b64 s[14:15], 0
	v_mov_b32_e32 v1, 0
	s_branch .LBB0_1068

.LBB0_1556:
	s_lshl_b32 s4, s65, 8
	s_add_u32 s4, s70, s4
	s_addc_u32 s5, s71, 0
	v_mov_b32_e32 v2, 0x1000
	v_mov_b32_e32 v4, 1
	global_atomic_add v4, v2, v4, s[4:5] offset:1024 sc0
	v_cvt_f32_u32_e32 v2, v3
	v_sub_u32_e32 v5, 0, v3
	v_rcp_iflag_f32_e32 v2, v2
	s_nop 0
	v_mul_f32_e32 v2, 0x4f7ffffe, v2
	v_cvt_u32_f32_e32 v2, v2
	v_mul_lo_u32 v5, v5, v2
	v_mul_hi_u32 v5, v2, v5
	v_add_u32_e32 v2, v2, v5
	s_waitcnt vmcnt(0)
	v_mul_hi_u32 v2, v4, v2
	v_mul_lo_u32 v5, v2, v3
	v_sub_u32_e32 v5, v4, v5
	v_add_u32_e32 v6, 1, v2
	v_cmp_ge_u32_e32 vcc, v5, v3
	v_add_u32_e32 v4, 1, v4
	s_nop 0
	v_cndmask_b32_e32 v2, v2, v6, vcc
	v_sub_u32_e32 v6, v5, v3
	v_cndmask_b32_e32 v5, v5, v6, vcc
	v_add_u32_e32 v6, 1, v2
	v_cmp_ge_u32_e32 vcc, v5, v3
	s_nop 1
	v_cndmask_b32_e32 v2, v2, v6, vcc
	v_mul_lo_u32 v5, v3, v2
	v_add_u32_e32 v3, v5, v3
	v_cmp_ne_u32_e32 vcc, v4, v3
	s_and_saveexec_b64 s[6:7], vcc
	s_xor_b64 s[6:7], exec, s[6:7]
	s_cbranch_execz .LBB0_1570
	s_waitcnt lgkmcnt(0)
	v_mov_b32_e32 v1, 0x3500
	global_load_dword v1, v1, s[70:71] sc1
	s_add_u32 s10, s70, 0x3500
	s_addc_u32 s11, s71, 0
	v_mov_b32_e32 v2, 12
	s_waitcnt vmcnt(0)
	v_cmp_eq_u32_e32 vcc, v1, v2
	s_and_saveexec_b64 s[8:9], vcc
	s_cbranch_execz .LBB0_1569
	s_mov_b32 s22, 1
	s_mov_b64 s[12:13], 0
	v_mov_b32_e32 v1, 0
	s_branch .LBB0_1560

	.amdhsa_kernel _Z6mk_fwd4Args
		.amdhsa_group_segment_fixed_size 0
		.amdhsa_private_segment_fixed_size 0
		.amdhsa_kernarg_size 440
		.amdhsa_user_sgpr_count 2
		.amdhsa_user_sgpr_dispatch_ptr 0
		.amdhsa_user_sgpr_queue_ptr 0
		.amdhsa_user_sgpr_kernarg_segment_ptr 1
		.amdhsa_user_sgpr_dispatch_id 0
		.amdhsa_user_sgpr_kernarg_preload_length 0
		.amdhsa_user_sgpr_kernarg_preload_offset 0
		.amdhsa_user_sgpr_private_segment_size 0
		.amdhsa_uses_dynamic_stack 0
		.amdhsa_enable_private_segment 0
		.amdhsa_system_sgpr_workgroup_id_x 1
		.amdhsa_system_sgpr_workgroup_id_y 0
		.amdhsa_system_sgpr_workgroup_id_z 0
		.amdhsa_system_sgpr_workgroup_info 0
		.amdhsa_system_vgpr_workitem_id 2
		.amdhsa_next_free_vgpr 256
		.amdhsa_next_free_sgpr 102
		.amdhsa_accum_offset 256
		.amdhsa_reserve_vcc 1
		.amdhsa_float_round_mode_32 0
		.amdhsa_float_round_mode_16_64 0
		.amdhsa_float_denorm_mode_32 3
		.amdhsa_float_denorm_mode_16_64 3
		.amdhsa_dx10_clamp 1
		.amdhsa_ieee_mode 1
		.amdhsa_fp16_overflow 0
		.amdhsa_tg_split 0
		.amdhsa_exception_fp_ieee_invalid_op 0
		.amdhsa_exception_fp_denorm_src 0
		.amdhsa_exception_fp_ieee_div_zero 0
		.amdhsa_exception_fp_ieee_overflow 0
		.amdhsa_exception_fp_ieee_underflow 0
		.amdhsa_exception_fp_ieee_inexact 0
		.amdhsa_exception_int_div_zero 0
	.end_amdhsa_kernel

amdhsa.kernels:
  - .agpr_count:     0
    .args:
      - .offset:         0
        .size:           184
        .value_kind:     by_value
      - .offset:         184
        .size:           4
        .value_kind:     hidden_block_count_x
      - .offset:         188
        .size:           4
        .value_kind:     hidden_block_count_y
      - .offset:         192
        .size:           4
        .value_kind:     hidden_block_count_z
      - .offset:         196
        .size:           2
        .value_kind:     hidden_group_size_x
      - .offset:         198
        .size:           2
        .value_kind:     hidden_group_size_y
      - .offset:         200
        .size:           2
        .value_kind:     hidden_group_size_z
      - .offset:         202
        .size:           2
        .value_kind:     hidden_remainder_x
      - .offset:         204
        .size:           2
        .value_kind:     hidden_remainder_y
      - .offset:         206
        .size:           2
        .value_kind:     hidden_remainder_z
      - .offset:         224
        .size:           8
        .value_kind:     hidden_global_offset_x
      - .offset:         232
        .size:           8
        .value_kind:     hidden_global_offset_y
      - .offset:         240
        .size:           8
        .value_kind:     hidden_global_offset_z
      - .offset:         248
        .size:           2
        .value_kind:     hidden_grid_dims
      - .offset:         272
        .size:           8
        .value_kind:     hidden_multigrid_sync_arg
      - .offset:         304
        .size:           4
        .value_kind:     hidden_dynamic_lds_size
    .group_segment_fixed_size: 0
    .kernarg_segment_align: 8
    .kernarg_segment_size: 440
    .language:       OpenCL C
    .language_version:
      - 2
      - 0
    .max_flat_workgroup_size: 512
    .name:           _Z6mk_fwd4Args
    .private_segment_fixed_size: 0
    .sgpr_count:     108
    .sgpr_spill_count: 59
    .symbol:         _Z6mk_fwd4Args.kd
    .uniform_work_group_size: 1
    .uses_dynamic_stack: false
    .vgpr_count:     256
    .vgpr_spill_count: 0
    .wavefront_size: 64
